# residual loads ahead of the closing workgroup barrier extended to both FFN-down variants (all four residual GEMM phases now prefetch the accumulator-init tile during the grid sync); rest as combined b
# speedup vs baseline: 1.0089x; 1.0036x over previous
; __device__ __forceinline__ float bf_lo(unsigned w) { return __uint_as_float(w << 16); }
; __device__ __forceinline__ float bf_hi(unsigned w) { return __uint_as_float(w & 0xffff0000u); }
; __device__ __forceinline__ int fresh_lane() { int l; asm volatile("v_mbcnt_lo_u32_b32 %0, -1, 0\n\tv_mbcnt_hi_u32_b32 %0, -1, %0" : "=v"(l)); return l; }
; __device__ __forceinline__ void acc_from_xb(AccT& acc, const bf16_t* xb, const Unit& u, int wr, int wc, int fr, int fq) {
;     const unsigned off0 = (unsigned)(u.pm * BM + wr * 64 + fr) * DM + u.pn * BM + wc * 32 + 8 * fq;
; #pragma unroll
;     for (int ai = 0; ai < 2; ++ai)
; #pragma unroll
;         for (int m = 0; m < 4; ++m)
; #pragma unroll
;             for (int bj = 0; bj < 2; ++bj) { const u32x4 w = *(const u32x4*)(xb + off0 + (unsigned)(ai * HALF + m * 16) * DM + bj * HALF);
;                 acc[ai][bj][m][0] = (f32x4){bf_lo(w.x), bf_hi(w.x), bf_lo(w.y), bf_hi(w.y)}; acc[ai][bj][m][1] = (f32x4){bf_lo(w.z), bf_hi(w.z), bf_lo(w.w), bf_hi(w.w)}; }
; template <class Epi, class Sched, bool ALIGN_EPI = false, bool SP2 = false>
; __device__ __forceinline__ void gemm_phase(PG8_LAS unsigned char* lds, const Gemm g, const Sched& S, const Epi& E, const int wid) {
;     const int lane = fresh_lane(), tid = wid * 64 + lane, wr = wid >> 2, wc = wid & 3, fr = lane & 15, fq = lane >> 4;
;     int nt = g.K / BK; asm volatile("" : "+s"(nt));
;     unsigned voffA[2], voffB[2];
; #pragma unroll
;     for (int i = 0; i < 2; ++i) { int R, C; stage_rc(tid * 16 + i * 8192, R, C); const int Rb = Epi::PERM ? ((R & ~31) + perm32(R & 31)) : R;
;         voffA[i] = (unsigned)(R * g.lda + C) * 2u; voffB[i] = (unsigned)(Rb * g.ldb + C) * 2u; }
;     const size_t kstep = (size_t)(BK * 2);
;     const size_t hstepA = (size_t)HALF * g.lda * 2, hstepB = (size_t)HALF * g.ldb * 2;
;     const size_t tstepA = 2 * hstepA, tstepB = 2 * hstepB;
;     const unsigned ldsw = (unsigned)wid * 1024u;
;     const int aoff = lds_byte(wr * 64 + fr, fq * 8), boff = lds_byte(wc * 32 + fr, fq * 8);
.LBB0_556:
	s_or_b64 exec, exec, s[4:5]
	s_and_b64 s[4:5], s[48:49], exec
	s_mov_b32 s4, 0x2600000
	s_cselect_b32 s4, s4, 0x2b80000
	s_add_u32 s64, s90, s4
	s_addc_u32 s65, s91, 0
	s_mov_b64 s[4:5], -1
	s_and_b64 vcc, exec, s[46:47]
	s_cbranch_vccz .LBB0_611
	v_readlane_b32 s8, v250, 33
	v_readlane_b32 s9, v250, 34
	s_mov_b32 s5, 44
	s_and_b64 vcc, exec, s[8:9]
	v_mbcnt_lo_u32_b32 v139, -1, 0
	v_mbcnt_hi_u32_b32 v139, -1, v139
	s_cbranch_vccz .Lrh_work_fda
	s_barrier
	s_branch .LBB0_610
.Lrh_work_fda:
	v_lshlrev_b32_e32 v140, 4, v139
	v_add_u32_e32 v1, s0, v140
	v_add_u32_e32 v2, 0x2000, v1
	v_ashrrev_i32_e32 v3, 31, v2
	v_lshrrev_b32_e32 v3, 22, v3
	v_add_u32_e32 v3, v2, v3
	v_ashrrev_i32_e32 v136, 10, v3
	v_mul_i32_i24_e32 v3, 0x400, v136
	v_sub_u32_e32 v2, v2, v3
	v_lshrrev_b32_e32 v3, 4, v2
	v_bitop3_b32 v2, v3, v2, 32 bitop3:0x6c
	v_ashrrev_i32_e32 v3, 31, v2
	v_lshrrev_b32_e32 v3, 26, v3
	v_add_u32_e32 v3, v2, v3
	v_ashrrev_i32_e32 v137, 6, v3
	v_lshlrev_b32_e32 v4, 3, v136
	v_and_b32_e32 v3, 0xffc0, v3
	v_and_b32_e32 v4, -16, v4
	v_sub_u32_e32 v2, v2, v3
	v_add_u32_e32 v4, v137, v4
	v_lshrrev_b16_e32 v3, 7, v2
	v_and_b32_e32 v5, 3, v137
	s_mov_b32 s4, 0xffffe0
	v_lshrrev_b32_e32 v6, 2, v4
	v_lshlrev_b32_e32 v7, 1, v4
	v_and_b32_e32 v3, 1, v3
	v_and_or_b32 v5, v4, s4, v5
	v_and_b32_e32 v6, 4, v6
	v_and_b32_e32 v7, 24, v7
	v_add_u16_e32 v2, v2, v3
	v_or3_b32 v5, v5, v6, v7
	v_lshlrev_b32_e32 v6, 5, v136
	v_ashrrev_i16_sdwa v2, v167, sext(v2) dst_sel:DWORD dst_unused:UNUSED_PAD src0_sel:DWORD src1_sel:BYTE_0
	v_and_b32_e32 v142, 32, v6
	v_bfe_i32 v143, v2, 0, 16
	s_movk_i32 s8, 0xb00
	v_mul_u32_u24_e32 v5, 0xb00, v5
	v_add_u32_e32 v2, v142, v143
	v_mul_lo_u32 v3, v4, s8
	v_add_lshl_u32 v128, v5, v2, 1
	v_add_lshl_u32 v130, v2, v3, 1
	v_ashrrev_i32_e32 v2, 31, v1
	v_lshrrev_b32_e32 v2, 22, v2
	v_add_u32_e32 v2, v1, v2
	v_ashrrev_i32_e32 v135, 10, v2
	v_mul_i32_i24_e32 v2, 0x400, v135
	v_sub_u32_e32 v1, v1, v2
	v_lshrrev_b32_e32 v2, 4, v1
	v_bitop3_b32 v1, v2, v1, 32 bitop3:0x6c
	v_ashrrev_i32_e32 v2, 31, v1
	v_lshrrev_b32_e32 v2, 26, v2
	v_add_u32_e32 v2, v1, v2
	v_lshlrev_b32_e32 v3, 3, v135
	v_ashrrev_i32_e32 v160, 6, v2
	v_and_b32_e32 v3, -16, v3
	v_add_u32_e32 v3, v160, v3
	v_and_b32_e32 v4, 3, v160
	v_lshrrev_b32_e32 v5, 2, v3
	v_lshlrev_b32_e32 v6, 1, v3
	v_and_b32_e32 v2, 0xc0, v2
	v_and_or_b32 v4, v3, s4, v4
	v_and_b32_e32 v5, 4, v5
	v_and_b32_e32 v6, 24, v6
	v_sub_u32_e32 v1, v1, v2
	v_or3_b32 v4, v4, v5, v6
	v_lshlrev_b32_e32 v5, 5, v135
	v_ashrrev_i16_sdwa v1, v167, sext(v1) dst_sel:DWORD dst_unused:UNUSED_PAD src0_sel:DWORD src1_sel:BYTE_0
	v_and_b32_e32 v161, 32, v5
	v_bfe_i32 v163, v1, 0, 16
	v_and_b32_e32 v134, 15, v139
	v_ashrrev_i32_e32 v0, 1, v139
	v_mul_u32_u24_e32 v4, 0xb00, v4
	v_add_u32_e32 v1, v161, v163
	v_mul_lo_u32 v2, v3, s8
	v_readlane_b32 s4, v249, 29
	v_and_b32_e32 v0, -8, v0
	v_add_lshl_u32 v146, v4, v1, 1
	v_add_lshl_u32 v132, v1, v2, 1
	v_or_b32_e32 v1, s4, v134
	v_readlane_b32 s4, v250, 32
	v_lshlrev_b32_e32 v1, 10, v1
	v_readlane_b32 s8, v249, 31
	v_add_u32_e32 v138, s4, v0
	v_readlane_b32 s4, v249, 30
	v_readlane_b32 s9, v249, 32
	s_nop 0
	v_add3_u32 v0, s4, v138, v1
	v_mov_b32_e32 v1, v147
	v_lshl_add_u64 v[0:1], v[0:1], 1, s[94:95]
	v_add_co_u32_e32 v2, vcc, s39, v0
	global_load_dwordx4 v[60:63], v[0:1], off
	global_load_dwordx4 v[56:59], v[0:1], off offset:256
	v_addc_co_u32_e32 v3, vcc, 0, v1, vcc
	global_load_dwordx4 v[52:55], v[2:3], off
	global_load_dwordx4 v[48:51], v[2:3], off offset:256
	v_add_co_u32_e32 v2, vcc, s52, v0
	s_mov_b32 s4, 0x40000
	s_nop 0
	v_addc_co_u32_e32 v3, vcc, 0, v1, vcc
	global_load_dwordx4 v[44:47], v[2:3], off
	global_load_dwordx4 v[40:43], v[2:3], off offset:256
	v_add_co_u32_e32 v2, vcc, s73, v0
	s_nop 1
	v_addc_co_u32_e32 v3, vcc, 0, v1, vcc
	global_load_dwordx4 v[32:35], v[2:3], off
	global_load_dwordx4 v[28:31], v[2:3], off offset:256
	v_add_co_u32_e32 v2, vcc, s4, v0
	s_mov_b32 s4, 0x48000
	s_nop 0
	v_addc_co_u32_e32 v3, vcc, 0, v1, vcc
	global_load_dwordx4 v[16:19], v[2:3], off
	global_load_dwordx4 v[12:15], v[2:3], off offset:256
	v_add_co_u32_e32 v2, vcc, s4, v0
	s_mov_b32 s4, 0x50000
	s_nop 0
	v_addc_co_u32_e32 v3, vcc, 0, v1, vcc
	global_load_dwordx4 v[4:7], v[2:3], off
	global_load_dwordx4 v[36:39], v[2:3], off offset:256
	v_add_co_u32_e32 v2, vcc, s4, v0
	s_mov_b32 s4, 0x58000
	s_nop 0
	v_addc_co_u32_e32 v3, vcc, 0, v1, vcc
	v_add_co_u32_e32 v0, vcc, s4, v0
	v_readlane_b32 s4, v248, 13
	s_add_u32 s10, s64, s4
	v_readlane_b32 s4, v248, 11
	s_addc_u32 s11, s65, s4
	s_add_i32 s67, s0, 0
	v_addc_co_u32_e32 v1, vcc, 0, v1, vcc
	s_add_i32 m0, s67, 0x10000
	global_load_dwordx4 v[24:27], v[2:3], off
	global_load_dwordx4 v[20:23], v[2:3], off offset:256
	global_load_dwordx4 v[8:11], v[0:1], off
	s_nop 0
	global_load_dwordx4 v[0:3], v[0:1], off offset:256
	s_nop 0
	s_barrier
	global_load_lds_dwordx4 v146, s[10:11]
	s_add_i32 m0, s67, 0x12000
	s_add_u32 s42, s10, 0xb0000
	global_load_lds_dwordx4 v128, s[10:11]
	s_addc_u32 s43, s11, 0
	s_add_i32 m0, s67, 0x14000
	s_add_i32 s68, s67, 0x2000
	global_load_lds_dwordx4 v146, s[42:43]
	s_add_i32 m0, s67, 0x16000
	s_add_i32 s69, s67, 0x4000
	global_load_lds_dwordx4 v128, s[42:43]
	s_mov_b32 m0, s67
	s_add_i32 s70, s67, 0x6000
	global_load_lds_dwordx4 v132, s[8:9]
	s_mov_b32 m0, s68
	s_nop 0
	global_load_lds_dwordx4 v130, s[8:9]
	v_readlane_b32 s8, v249, 33
	s_mov_b32 m0, s69
	v_readlane_b32 s9, v249, 34
	s_nop 4
	global_load_lds_dwordx4 v132, s[8:9]
	s_mov_b32 m0, s70
	s_nop 0
	global_load_lds_dwordx4 v130, s[8:9]
	v_readlane_b32 s8, v248, 1
	v_readlane_b32 s9, v248, 2
	s_andn2_b64 vcc, exec, s[8:9]
	s_cbranch_vccnz .LBB0_560
	s_barrier

; __device__ __forceinline__ void acc_from_xb(AccT& acc, const bf16_t* xb, const Unit& u, int wr, int wc, int fr, int fq) {
;     const unsigned off0 = (unsigned)(u.pm * BM + wr * 64 + fr) * DM + u.pn * BM + wc * 32 + 8 * fq;
; #pragma unroll
;     for (int ai = 0; ai < 2; ++ai)
; #pragma unroll
; template <class Epi, class Sched, bool ALIGN_EPI = false, bool SP2 = false>
; __device__ __forceinline__ void gemm_phase(PG8_LAS unsigned char* lds, const Gemm g, const Sched& S, const Epi& E, const int wid) {
;     const int lane = fresh_lane(), tid = wid * 64 + lane, wr = wid >> 2, wc = wid & 3, fr = lane & 15, fq = lane >> 4;
;     int nt = g.K / BK; asm volatile("" : "+s"(nt));
;     unsigned voffA[2], voffB[2];
; #pragma unroll
;     for (int i = 0; i < 2; ++i) { int R, C; stage_rc(tid * 16 + i * 8192, R, C); const int Rb = Epi::PERM ? ((R & ~31) + perm32(R & 31)) : R;
;         voffA[i] = (unsigned)(R * g.lda + C) * 2u; voffB[i] = (unsigned)(Rb * g.ldb + C) * 2u; }
;     const size_t kstep = (size_t)(BK * 2);
;     const size_t hstepA = (size_t)HALF * g.lda * 2, hstepB = (size_t)HALF * g.ldb * 2;
;     const size_t tstepA = 2 * hstepA, tstepB = 2 * hstepB;
;     const unsigned ldsw = (unsigned)wid * 1024u;
;     const int aoff = lds_byte(wr * 64 + fr, fq * 8), boff = lds_byte(wc * 32 + fr, fq * 8);
;     ...
;     Unit cur, nxt; int ui = 0;
;     if (!S.next(0, cur)) return;
;     f32x4 acc[2][2][4][2];
;     if constexpr (Epi::ACC_INIT) E.init(acc, cur, wr, wc, fr, fq);
;     else {
; #pragma unroll
;     for (int a = 0; a < 2; ++a)
; #pragma unroll
;         for (int b = 0; b < 2; ++b)
; #pragma unroll
;             for (int m = 0; m < 4; ++m)
; #pragma unroll
;                 for (int n = 0; n < 2; ++n) acc[a][b][m][n] = (f32x4){0.f, 0.f, 0.f, 0.f};
;     }
;     bf16x8 At[4][2], B0[2][2], B1[2][2];
;     const char* cA = cur.pn >= g.swap_pn ? (const char*)g.A2 + (size_t)(cur.pn - g.swap_pn) * tstepA : (const char*)g.A + (size_t)cur.pm * tstepA + (g.bd ? (size_t)(cur.pn >> 1) * 512 : 0);
;     const char* cB = cur.pn >= g.swap_pn ? (const char*)g.B2 + (size_t)cur.pm * tstepB : (const char*)g.Bt + (size_t)cur.pn * tstepB;
;     S.a_ready(cur);
;     if constexpr (SP2) {
;         PG8_STAGE(PG8_SB(0, 0), cB, voffB); PG8_STAGE(PG8_SB(0, 1), cB + hstepB, voffB); PG8_STAGE(PG8_SA(0, 0), cA, voffA); PG8_STAGE(PG8_SA(0, 1), cA + hstepA, voffA);
.LBB0_611:
	s_andn2_b64 vcc, exec, s[4:5]
	s_cbranch_vccnz .LBB0_654
	v_readlane_b32 s8, v250, 33
	v_readlane_b32 s9, v250, 34
	s_mov_b32 s5, 44
	s_and_b64 vcc, exec, s[8:9]
	v_mbcnt_lo_u32_b32 v138, -1, 0
	v_mbcnt_hi_u32_b32 v138, -1, v138
	s_cbranch_vccz .Lrh_work_fdb
	s_barrier
	s_branch .LBB0_654
.Lrh_work_fdb:
	v_lshlrev_b32_e32 v139, 4, v138
	v_add_u32_e32 v1, s0, v139
	v_add_u32_e32 v2, 0x2000, v1
	v_ashrrev_i32_e32 v3, 31, v2
	v_lshrrev_b32_e32 v3, 22, v3
	v_add_u32_e32 v3, v2, v3
	v_ashrrev_i32_e32 v136, 10, v3
	v_mul_i32_i24_e32 v3, 0x400, v136
	v_sub_u32_e32 v2, v2, v3
	v_lshrrev_b32_e32 v3, 4, v2
	v_bitop3_b32 v2, v3, v2, 32 bitop3:0x6c
	v_ashrrev_i32_e32 v3, 31, v2
	v_lshrrev_b32_e32 v3, 26, v3
	v_add_u32_e32 v3, v2, v3
	v_ashrrev_i32_e32 v137, 6, v3
	v_lshlrev_b32_e32 v4, 3, v136
	v_and_b32_e32 v3, 0xffc0, v3
	v_and_b32_e32 v4, -16, v4
	v_sub_u32_e32 v2, v2, v3
	v_add_u32_e32 v4, v137, v4
	v_lshrrev_b16_e32 v3, 7, v2
	v_and_b32_e32 v5, 3, v137
	s_mov_b32 s4, 0xffffe0
	v_lshrrev_b32_e32 v6, 2, v4
	v_lshlrev_b32_e32 v7, 1, v4
	v_and_b32_e32 v3, 1, v3
	v_and_or_b32 v5, v4, s4, v5
	v_and_b32_e32 v6, 4, v6
	v_and_b32_e32 v7, 24, v7
	v_add_u16_e32 v2, v2, v3
	v_or3_b32 v5, v5, v6, v7
	v_lshlrev_b32_e32 v6, 5, v136
	v_ashrrev_i16_sdwa v2, v167, sext(v2) dst_sel:DWORD dst_unused:UNUSED_PAD src0_sel:DWORD src1_sel:BYTE_0
	v_and_b32_e32 v143, 32, v6
	v_bfe_i32 v160, v2, 0, 16
	s_movk_i32 s8, 0xb00
	v_mul_u32_u24_e32 v5, 0xb00, v5
	v_add_u32_e32 v2, v143, v160
	v_mul_lo_u32 v3, v4, s8
	v_add_lshl_u32 v128, v5, v2, 1
	v_add_lshl_u32 v130, v2, v3, 1
	v_ashrrev_i32_e32 v2, 31, v1
	v_lshrrev_b32_e32 v2, 22, v2
	v_add_u32_e32 v2, v1, v2
	v_ashrrev_i32_e32 v134, 10, v2
	v_mul_i32_i24_e32 v2, 0x400, v134
	v_sub_u32_e32 v1, v1, v2
	v_lshrrev_b32_e32 v2, 4, v1
	v_bitop3_b32 v1, v2, v1, 32 bitop3:0x6c
	v_ashrrev_i32_e32 v2, 31, v1
	v_lshrrev_b32_e32 v2, 26, v2
	v_add_u32_e32 v2, v1, v2
	v_lshlrev_b32_e32 v3, 3, v134
	v_ashrrev_i32_e32 v135, 6, v2
	v_and_b32_e32 v3, -16, v3
	v_add_u32_e32 v3, v135, v3
	v_and_b32_e32 v4, 3, v135
	v_lshrrev_b32_e32 v5, 2, v3
	v_lshlrev_b32_e32 v6, 1, v3
	v_and_b32_e32 v2, 0xc0, v2
	v_and_or_b32 v4, v3, s4, v4
	v_and_b32_e32 v5, 4, v5
	v_and_b32_e32 v6, 24, v6
	v_sub_u32_e32 v1, v1, v2
	v_or3_b32 v4, v4, v5, v6
	v_lshlrev_b32_e32 v5, 5, v134
	v_ashrrev_i16_sdwa v1, v167, sext(v1) dst_sel:DWORD dst_unused:UNUSED_PAD src0_sel:DWORD src1_sel:BYTE_0
	v_and_b32_e32 v161, 32, v5
	v_bfe_i32 v162, v1, 0, 16
	v_and_b32_e32 v140, 15, v138
	v_ashrrev_i32_e32 v0, 1, v138
	v_mul_u32_u24_e32 v4, 0xb00, v4
	v_add_u32_e32 v1, v161, v162
	v_mul_lo_u32 v2, v3, s8
	v_readlane_b32 s4, v249, 29
	v_and_b32_e32 v0, -8, v0
	v_add_lshl_u32 v146, v4, v1, 1
	v_add_lshl_u32 v132, v1, v2, 1
	v_or_b32_e32 v1, s4, v140
	v_readlane_b32 s4, v250, 32
	v_lshlrev_b32_e32 v1, 10, v1
	v_readlane_b32 s8, v249, 31
	v_add_u32_e32 v141, s4, v0
	v_readlane_b32 s4, v249, 30
	v_readlane_b32 s9, v249, 32
	s_nop 0
	v_add3_u32 v0, s4, v141, v1
	v_mov_b32_e32 v1, v147
	v_lshl_add_u64 v[4:5], v[0:1], 1, s[94:95]
	v_add_co_u32_e32 v0, vcc, s39, v4
	global_load_dwordx4 v[60:63], v[4:5], off
	global_load_dwordx4 v[56:59], v[4:5], off offset:256
	v_addc_co_u32_e32 v1, vcc, 0, v5, vcc
	global_load_dwordx4 v[52:55], v[0:1], off
	global_load_dwordx4 v[48:51], v[0:1], off offset:256
	v_add_co_u32_e32 v0, vcc, s52, v4
	s_mov_b32 s4, 0x40000
	s_nop 0
	v_addc_co_u32_e32 v1, vcc, 0, v5, vcc
	global_load_dwordx4 v[44:47], v[0:1], off
	global_load_dwordx4 v[40:43], v[0:1], off offset:256
	v_add_co_u32_e32 v0, vcc, s73, v4
	s_nop 1
	v_addc_co_u32_e32 v1, vcc, 0, v5, vcc
	global_load_dwordx4 v[24:27], v[0:1], off
	global_load_dwordx4 v[20:23], v[0:1], off offset:256
	v_add_co_u32_e32 v0, vcc, s4, v4
	s_mov_b32 s4, 0x48000
	s_nop 0
	v_addc_co_u32_e32 v1, vcc, 0, v5, vcc
	v_add_co_u32_e32 v6, vcc, s4, v4
	s_mov_b32 s4, 0x50000
	s_nop 0
	v_addc_co_u32_e32 v7, vcc, 0, v5, vcc
	global_load_dwordx4 v[16:19], v[0:1], off
	global_load_dwordx4 v[12:15], v[0:1], off offset:256
	s_nop 0
	global_load_dwordx4 v[0:3], v[6:7], off
	global_load_dwordx4 v[36:39], v[6:7], off offset:256
	v_add_co_u32_e32 v6, vcc, s4, v4
	s_mov_b32 s4, 0x58000
	s_nop 0
	v_addc_co_u32_e32 v7, vcc, 0, v5, vcc
	v_add_co_u32_e32 v4, vcc, s4, v4
	v_readlane_b32 s4, v248, 13
	s_add_u32 s10, s64, s4
	v_readlane_b32 s4, v248, 11
	s_addc_u32 s11, s65, s4
	s_add_i32 s66, s0, 0
	v_addc_co_u32_e32 v5, vcc, 0, v5, vcc
	s_add_i32 m0, s66, 0x10000
	global_load_dwordx4 v[32:35], v[6:7], off
	global_load_dwordx4 v[28:31], v[6:7], off offset:256
	global_load_dwordx4 v[8:11], v[4:5], off
	s_nop 0
	global_load_dwordx4 v[4:7], v[4:5], off offset:256
	s_nop 0
	s_barrier
	global_load_lds_dwordx4 v146, s[10:11]
	s_add_i32 m0, s66, 0x12000
	s_add_u32 s42, s10, 0xb0000
	global_load_lds_dwordx4 v128, s[10:11]
	s_addc_u32 s43, s11, 0
	s_add_i32 m0, s66, 0x14000
	s_add_i32 s67, s66, 0x2000
	global_load_lds_dwordx4 v146, s[42:43]
	s_add_i32 m0, s66, 0x16000
	s_add_i32 s68, s66, 0x4000
	global_load_lds_dwordx4 v128, s[42:43]
	s_mov_b32 m0, s66
	s_add_i32 s69, s66, 0x6000
	global_load_lds_dwordx4 v132, s[8:9]
	s_mov_b32 m0, s67
	s_nop 0
	global_load_lds_dwordx4 v130, s[8:9]
	v_readlane_b32 s8, v249, 33
	s_mov_b32 m0, s68
	v_readlane_b32 s9, v249, 34
	s_nop 4
	global_load_lds_dwordx4 v132, s[8:9]
	s_mov_b32 m0, s69
	s_nop 0
	global_load_lds_dwordx4 v130, s[8:9]
	v_readlane_b32 s8, v248, 1
	v_readlane_b32 s9, v248, 2
	s_andn2_b64 vcc, exec, s[8:9]
	s_cbranch_vccnz .LBB0_615
	s_barrier
